# LDS bank-conflict lever: K/V tile chunks XOR-swizzled per row so the K-fragment ds_read_b128 lane groups hit distinct banks
# speedup vs baseline: 1.0014x; 1.0014x over previous
; #define GAS __attribute__((address_space(1)))
; #define LAS __attribute__((address_space(3)))
; template <bool MASKED>
; __device__ __forceinline__ void qk_softmax(const LAS bf16_t* Kt, const bf16x8 (&qf)[3][2], float (&m)[3], f32x4 (&lacc)[3], f32x4 (&acc)[3][4], unsigned& started,
;                                            bool act, int hi, int lo, int lr, int q, bf16x8 (&pb)[3][2]) {
;     const LAS bf16_t* kbase = Kt + lr * 72 + 8 * q;
; __device__ __forceinline__ void nsa_phase(LAS unsigned char* lds, const bf16_t* Q, const bf16_t* KVG, size_t kvg_stride, const bf16_t* kcc, const bf16_t* vcc, const float* G, bf16_t* cat,
;                                           int tid, int lane, int wave) {
;     ...
;     for (int u = blockIdx.x; u < 2048; u += gridDim.x) {
;         const int rnd = u >> 8, cc = u & 255, xq = cc & 7, bg = 4 * rnd + (xq >> 1), ii = (xq & 1) * 32 + (cc >> 3), iq = (rnd & 1) ? 63 - ii : ii;
;         const int b = bg >> 2, g = bg & 3, t0 = 128 * iq;
;         int lane_u; asm volatile("v_mbcnt_lo_u32_b32 %0, -1, 0\n\tv_mbcnt_hi_u32_b32 %0, -1, %0" : "=&v"(lane_u));
;         const int lr = lane_u & 15, q = lane_u >> 4;
;         const int t = t0 + 16 * wave + lr; const size_t rowu = (size_t)b * SEQ + t0; const unsigned tl = (unsigned)(16 * wave + lr);
;         const bf16_t* Qp = Q + rowu * 768 + 3 * g * 64; const float* Gp = G + rowu * 36 + 9 * g; bf16_t* catp = cat + rowu * 1024 + 3 * g * 64;
;         bf16x8 qf[3][2];
; #pragma unroll
;         for (int r = 0; r < 3; ++r)
; #pragma unroll
;             for (int ks = 0; ks < 2; ++ks) qf[r][ks] = *(const GAS bf16x8*)(Qp + (tl * 768u + (unsigned)(r * 64 + 32 * ks + 8 * q)));
;         const int ntc = (8 * iq + 7 + 63) >> 6;
;         const int cmaxv = (t - 31) >> 4;
; #pragma unroll 1
;         for (int br = 0; br < 3; ++br) {
;             const bf16_t* gK; const bf16_t* gV; int nbeg, nend, hbase;
;             if (br == 0) { gK = kcc + (size_t)bg * 512 * 64; gV = vcc + (size_t)bg * 512 * 64; nbeg = 0; nend = ntc; hbase = cmaxv; }
;             else { gK = KVG + (size_t)(2 * br) * kvg_stride + (size_t)bg * SEQ * 64; gV = gK + kvg_stride; nbeg = (br == 2 && 2 * iq - 8 > 0) ? 2 * iq - 8 : 0; nend = 2 * iq + 2; hbase = t; }
.LBB0_947:
	s_lshl_b32 s2, s5, 5
	s_and_b32 s2, s2, 32
	s_bfe_u32 s3, s5, 0x50003
	s_or_b32 s2, s2, s3
	s_ashr_i32 s6, s5, 6
	s_bfe_u32 s7, s5, 0x20001
	s_and_b32 s3, s5, 0x100
	s_xor_b32 s4, s2, 63
	s_cmp_eq_u32 s3, 0
	s_cselect_b32 s8, s2, s4
	s_ashr_i32 s2, s5, 8
	s_ashr_i32 s3, s2, 31
	v_writelane_b32 v255, s5, 42
	s_lshl_b32 s9, s8, 7
	s_lshl_b64 s[4:5], s[2:3], 13
	s_or_b32 s4, s4, s9
	s_mul_hi_u32 s3, s4, 0x600
	s_mul_i32 s10, s5, 0x600
	s_add_i32 s14, s9, s26
	s_mul_i32 s2, s4, 0x600
	s_add_i32 s3, s3, s10
	v_readlane_b32 s10, v255, 25
	v_mbcnt_lo_u32_b32 v204, -1, 0
	v_mbcnt_hi_u32_b32 v204, -1, v204
	s_add_u32 s2, s10, s2
	v_and_b32_e32 v24, 15, v204
	v_readlane_b32 s10, v255, 26
	s_waitcnt vmcnt(0)
	v_or_b32_e32 v0, s26, v24
	s_addc_u32 s3, s10, s3
	s_mul_i32 s10, s7, 0x180
	v_ashrrev_i32_e32 v25, 4, v204
	s_add_u32 s2, s2, s10
	v_mul_lo_u32 v0, v0, s48
	s_addc_u32 s3, s3, 0
	v_lshl_add_u32 v190, v25, 3, v0
	v_lshl_add_u64 v[0:1], v[190:191], 1, s[2:3]
	v_add_u32_e32 v2, 32, v190
	v_mov_b32_e32 v3, v191
	v_add_u32_e32 v8, 64, v190
	v_mov_b32_e32 v9, v191
	v_add_u32_e32 v10, 0x60, v190
	v_mov_b32_e32 v11, v191
	v_add_u32_e32 v16, 0x80, v190
	v_mov_b32_e32 v17, v191
	v_add_u32_e32 v190, 0xa0, v190
	v_lshl_add_u64 v[4:5], v[2:3], 1, s[2:3]
	v_lshl_add_u64 v[8:9], v[8:9], 1, s[2:3]
	v_lshl_add_u64 v[12:13], v[10:11], 1, s[2:3]
	v_lshl_add_u64 v[16:17], v[16:17], 1, s[2:3]
	v_lshl_add_u64 v[20:21], v[190:191], 1, s[2:3]
	global_load_dwordx4 v[0:3], v[0:1], off
	s_nop 0
	global_load_dwordx4 v[4:7], v[4:5], off
	s_nop 0
	global_load_dwordx4 v[8:11], v[8:9], off
	s_nop 0
	global_load_dwordx4 v[12:15], v[12:13], off
	s_nop 0
	global_load_dwordx4 v[16:19], v[16:17], off
	s_nop 0
	global_load_dwordx4 v[20:23], v[20:21], off
	s_mul_hi_u32 s12, s4, 0x90
	s_mul_i32 s13, s5, 0x90
	s_mul_i32 s11, s4, 0x90
	s_add_i32 s12, s12, s13
	s_lshl_b64 s[4:5], s[4:5], 11
	v_readlane_b32 s13, v255, 35
	s_add_u32 s13, s13, s4
	v_readlane_b32 s4, v255, 36
	s_addc_u32 s5, s4, s5
	s_and_b32 s4, s6, -4
	s_or_b32 s4, s4, s7
	v_readlane_b32 s6, v255, 33
	s_add_u32 s6, s6, s11
	v_readlane_b32 s11, v255, 34
	s_addc_u32 s11, s11, s12
	s_mul_i32 s7, s7, 36
	s_add_u32 s24, s6, s7
	s_addc_u32 s25, s11, 0
	s_add_u32 s20, s13, s10
	s_addc_u32 s21, s5, 0
	s_lshl_b32 s5, s8, 3
	s_add_i32 s10, s5, 0x46
	s_ashr_i32 s5, s4, 31
	s_lshr_b32 s40, s10, 6
	s_lshl_b64 s[6:7], s[4:5], 20
	v_readlane_b32 s11, v255, 27
	s_add_u32 s15, s11, s6
	v_readlane_b32 s6, v255, 28
	s_addc_u32 s56, s6, s7
	s_cmp_gt_u32 s8, 4
	s_cselect_b64 s[50:51], -1, 0
	s_lshl_b32 s44, s8, 1
	s_add_i32 s52, s44, -8
	s_add_i32 s44, s44, 2
	s_lshl_b64 s[4:5], s[4:5], 16
	v_readlane_b32 s6, v255, 29
	s_add_u32 s28, s6, s4
	v_readlane_b32 s6, v255, 30
	s_addc_u32 s29, s6, s5
	v_readlane_b32 s6, v255, 31
	s_add_u32 s82, s6, s4
	v_readlane_b32 s4, v255, 32
	s_addc_u32 s83, s4, s5
	v_readlane_b32 s4, v255, 38
	v_lshlrev_b32_e32 v210, 2, v25
	v_bfe_u32 v25, v204, 2, 2
	s_ashr_i32 s45, s14, 6
	v_add_u32_e32 v207, s4, v204
	v_or_b32_e32 v25, v210, v25
	s_movk_i32 s4, 0x90
	s_cmp_gt_i32 s45, 15
	v_mul_lo_u32 v211, v25, s4
	v_writelane_b32 v255, s14, 43
	s_cselect_b64 s[4:5], -1, 0
	v_writelane_b32 v255, s4, 44
	s_add_i32 s46, s45, -2
	s_lshr_b32 s57, s45, 5
	v_writelane_b32 v255, s5, 45
	s_lshl_b32 s4, 1, s45
	v_writelane_b32 v255, s4, 46
	s_add_i32 s4, s45, -1
	s_lshr_b32 s5, s4, 5
	v_writelane_b32 v255, s5, 47
	s_lshl_b32 s4, 1, s4
	v_writelane_b32 v255, s4, 48
	s_add_i32 s4, s45, 1
	s_lshl_b32 s4, -1, s4
	s_not_b32 s4, s4
	v_writelane_b32 v255, s4, 49
	v_or_b32_e32 v205, s14, v24
	v_readlane_b32 s4, v255, 39
	s_add_u32 s30, s2, s4
	s_mul_hi_i32 s2, s26, 0x600
	s_addc_u32 s31, s3, s2
	s_movk_i32 s2, 0x2f0
	v_cmp_gt_i32_e64 s[58:59], s2, v204
	s_movk_i32 s2, 0x2b0
	v_cmp_gt_i32_e64 s[60:61], s2, v204
	s_movk_i32 s2, 0x270
	v_cmp_gt_i32_e64 s[62:63], s2, v204
	s_movk_i32 s2, 0x230
	v_cmp_gt_i32_e64 s[64:65], s2, v204
	s_movk_i32 s2, 0x1f0
	v_cmp_gt_i32_e64 s[66:67], s2, v204
	s_movk_i32 s2, 0x1b0
	v_cmp_gt_i32_e64 s[2:3], s2, v204
	v_subrev_u32_e32 v26, 31, v205
	v_lshlrev_b32_e32 v25, 2, v204
	v_writelane_b32 v255, s2, 50
	v_ashrrev_i32_e32 v206, 4, v26
	v_and_b32_e32 v25, 12, v25
	v_writelane_b32 v255, s3, 51
	s_movk_i32 s2, 0x170
	v_cmp_gt_i32_e64 s[2:3], s2, v204
	v_lshlrev_b32_e32 v26, 4, v204
	s_mov_b32 s42, 0
	v_writelane_b32 v255, s2, 52
	v_mul_u32_u24_e32 v208, 0x90, v24
	v_and_b32_e32 v209, -16, v204
	v_add_u32_e32 v214, 4, v204
	v_and_b32_e32 v214, 8, v214
	v_lshlrev_b32_e32 v214, 1, v214
	v_xor_b32_e32 v209, v209, v214
	v_writelane_b32 v255, s3, 53
	s_movk_i32 s2, 0x130
	v_cmp_gt_i32_e64 s[2:3], s2, v204
	v_cmp_gt_i32_e64 s[54:55], s41, v204
	v_sub_u32_e32 v213, 0, v210
	v_writelane_b32 v255, s2, 54
	s_and_b32 s47, s10, 0x3c0
	v_lshlrev_b32_e32 v214, 1, v25
	v_lshrrev_b32_e32 v215, 2, v204
	v_add_u32_e32 v215, 4, v215
	v_and_b32_e32 v215, 8, v215
	v_lshlrev_b32_e32 v215, 1, v215
	v_xor_b32_e32 v214, v214, v215
	v_writelane_b32 v255, s3, 55
	s_movk_i32 s2, 0xf0
	v_cmp_gt_i32_e64 s[2:3], s2, v204
	v_add_u32_e32 v215, s49, v26
	s_nop 0
	v_writelane_b32 v255, s2, 56
	s_nop 1
	v_writelane_b32 v255, s3, 57
	s_movk_i32 s2, 0xb0
	v_cmp_gt_i32_e64 s[2:3], s2, v204
	s_nop 1
	v_writelane_b32 v255, s2, 58
	s_nop 1
	v_writelane_b32 v255, s3, 59
	s_movk_i32 s2, 0x70
	v_cmp_gt_i32_e64 s[2:3], s2, v204
	s_nop 1
	v_writelane_b32 v255, s2, 60
	s_nop 1
	v_writelane_b32 v255, s3, 61
	s_nop 0
	v_readlane_b32 s2, v255, 40
	s_add_i32 s2, s2, s9
	s_nop 0
	v_add_u32_e32 v212, s2, v24
	v_cmp_gt_i32_e64 s[2:3], 48, v204
	s_nop 1
	v_writelane_b32 v255, s2, 62
	s_nop 1
	v_writelane_b32 v255, s3, 63
	s_branch .LBB0_950

; #define LAS __attribute__((address_space(3)))
; __device__ __forceinline__ void kv_commit(const KVRegs& R, LAS bf16_t* Kt, LAS bf16_t* Vt, int tid, bool withv) {
;     const int key = tid >> 3, dc = tid & 7;
;     *(LAS u32x4*)(Kt + key * 72 + dc * 8) = R.k;
;     if (withv) *(LAS u32x4*)(Vt + key * 72 + dc * 8) = R.v;
; __device__ __forceinline__ void nsa_phase(LAS unsigned char* lds, const bf16_t* Q, const bf16_t* KVG, size_t kvg_stride, const bf16_t* kcc, const bf16_t* vcc, const float* G, bf16_t* cat,
;                                           int tid, int lane, int wave) {
;     ...
;             float zf_ = 0.f; asm volatile("" : "+v"(zf_));
;             float m[3]; f32x4 lacc[3]; f32x4 acc[3][4]; unsigned started = __float_as_uint(zf_);
; #pragma unroll
;             for (int r = 0; r < 3; ++r) { m[r] = zf_; lacc[r] = (f32x4){zf_, zf_, zf_, zf_};
; #pragma unroll
;                 for (int dt = 0; dt < 4; ++dt) acc[r][dt] = (f32x4){zf_, zf_, zf_, zf_}; }
;             KVRegs R;
;             __syncthreads();
;             int tb = wave * 64 + lane_u; asm volatile("" : "+v"(tb));
;             kv_fetch(R, gK + (size_t)nbeg * 4096, gV + (size_t)nbeg * 4096, tb, true);
;             int kc_ = 0;
;             for (int n = nbeg; n < nend; ++n) {
;                 LAS bf16_t* Kt = Kb0 + kc_ * 64 * 72; LAS bf16_t* Vt = Vb0 + kc_ * 64 * 72;
;                 kv_commit(R, Kt, Vt, tb, true);
.LBB0_954:
	v_mov_b32_e32 v72, 0
	v_mov_b32_e32 v24, v207
	v_mov_b32_e32 v73, v72
	v_mov_b32_e32 v74, v72
	v_mov_b32_e32 v75, v72
	s_cmp_ge_i32 s38, s43
	s_waitcnt lgkmcnt(0)
	s_barrier
	s_cbranch_scc1 .LBB0_984
	s_lshl_b64 s[4:5], s[38:39], 13
	v_lshlrev_b32_e32 v26, 3, v24
	s_add_u32 s6, s34, s4
	v_ashrrev_i32_e32 v27, 31, v26
	s_addc_u32 s7, s35, s5
	v_lshlrev_b64 v[28:29], 1, v[26:27]
	s_add_u32 s4, s10, s4
	v_lshl_add_u64 v[30:31], s[6:7], 0, v[28:29]
	s_addc_u32 s5, s11, s5
	global_load_dwordx4 v[76:79], v[30:31], off
	v_lshl_add_u64 v[30:31], s[4:5], 0, v[28:29]
	global_load_dwordx4 v[80:83], v[30:31], off
	v_lshrrev_b32_e32 v24, 3, v24
	s_movk_i32 s4, 0x48
	s_cmp_eq_u32 s42, 2
	v_mul_lo_u32 v30, v24, s4
	s_cselect_b64 s[68:69], -1, 0
	s_lshl_b32 s4, s38, 6
	s_mov_b64 s[36:37], s[82:83]
	s_mov_b64 s[82:83], s[28:29]
	s_mov_b64 s[28:29], s[66:67]
	s_mov_b64 s[66:67], s[64:65]
	s_mov_b64 s[64:65], s[62:63]
	s_mov_b64 s[62:63], s[60:61]
	s_mov_b64 s[60:61], s[58:59]
	s_mov_b64 s[58:59], s[54:55]
	s_mov_b64 s[54:55], s[50:51]
	s_sub_i32 s50, 0, s4
	s_ashr_i32 s5, s38, 31
	s_mov_b32 s4, s38
	s_lshl_b64 s[4:5], s[4:5], 13
	v_lshl_add_u64 v[24:25], s[4:5], 0, v[28:29]
	v_and_b32_e32 v31, 56, v26
	v_lshl_add_u64 v[26:27], s[10:11], 0, v[24:25]
	v_lshl_add_u64 v[24:25], s[34:35], 0, v[24:25]
	v_lshl_add_u64 v[200:201], v[26:27], 0, s[22:23]
	v_lshl_add_u64 v[202:203], v[24:25], 0, s[22:23]
	v_lshlrev_b32_e32 v217, 1, v30
	v_lshlrev_b32_e32 v218, 1, v31
	v_lshrrev_b32_e32 v86, 3, v207
	v_add_u32_e32 v86, 4, v86
	v_and_b32_e32 v86, 8, v86
	v_lshlrev_b32_e32 v86, 1, v86
	v_xor_b32_e32 v218, v218, v86
	v_mov_b64_e32 v[86:87], v[74:75]
	v_mov_b64_e32 v[90:91], v[74:75]
	v_mov_b64_e32 v[94:95], v[74:75]
	v_mov_b64_e32 v[24:25], v[72:73]
	v_mov_b64_e32 v[28:29], v[72:73]
	v_mov_b64_e32 v[32:33], v[72:73]
	v_mov_b64_e32 v[36:37], v[72:73]
	v_mov_b64_e32 v[40:41], v[72:73]
	v_mov_b64_e32 v[44:45], v[72:73]
	v_mov_b64_e32 v[48:49], v[72:73]
	v_mov_b64_e32 v[52:53], v[72:73]
	v_mov_b64_e32 v[56:57], v[72:73]
	v_mov_b64_e32 v[60:61], v[72:73]
	v_mov_b64_e32 v[64:65], v[72:73]
	v_mov_b64_e32 v[68:69], v[72:73]
	s_mov_b32 s53, s52
	s_mov_b32 s52, s15
	s_mov_b32 s41, 0
	v_add_u32_e32 v216, v213, v190
	v_mov_b32_e32 v219, v212
	v_mov_b64_e32 v[84:85], v[72:73]
	v_mov_b64_e32 v[88:89], v[72:73]
	v_mov_b64_e32 v[92:93], v[72:73]
	v_mov_b64_e32 v[26:27], v[74:75]
	v_mov_b64_e32 v[30:31], v[74:75]
	v_mov_b64_e32 v[34:35], v[74:75]
	v_mov_b64_e32 v[38:39], v[74:75]
	v_mov_b64_e32 v[42:43], v[74:75]
	v_mov_b64_e32 v[46:47], v[74:75]
	v_mov_b64_e32 v[50:51], v[74:75]
	v_mov_b64_e32 v[54:55], v[74:75]
	v_mov_b64_e32 v[58:59], v[74:75]
	v_mov_b64_e32 v[62:63], v[74:75]
	v_mov_b64_e32 v[66:67], v[74:75]
	v_mov_b64_e32 v[70:71], v[74:75]
	v_mov_b32_e32 v226, v72
	v_mov_b32_e32 v227, v72
	v_mov_b32_e32 v228, v72
	s_mov_b32 s51, s38
	v_mov_b32_e32 v229, v72

; #define GAS __attribute__((address_space(1)))
; #define LAS __attribute__((address_space(3)))
; #define MFMA16(a, b, c) __builtin_amdgcn_mfma_f32_16x16x32_bf16((a), (b), (c), 0, 0, 0)
; __device__ __forceinline__ void tile_importance(const LAS bf16_t* Kt, const bf16x8 (&qf)[3][2], const float (&m)[3], const float (&invl)[3], int hi, LAS float* imp, int tt, int lr, int q) {
;     ...
;             for (int ks = 0; ks < 2; ++ks) { const bf16x8 kf = *(const LAS bf16x8*)(Kt + (16 * mt + lr) * 72 + 32 * ks + 8 * q); s = MFMA16(kf, qf[r][ks], s); }
; __device__ __forceinline__ void nsa_phase(LAS unsigned char* lds, const bf16_t* Q, const bf16_t* KVG, size_t kvg_stride, const bf16_t* kcc, const bf16_t* vcc, const float* G, bf16_t* cat,
;                                           int tid, int lane, int wave) {
;     ...
;             float invl[3];
; #pragma unroll
;             for (int r = 0; r < 3; ++r) { const float lt = lacc[r][0]; invl[r] = lt > 0.f ? __builtin_amdgcn_rcpf(lt) : 0.f; }
;             if (br == 0) {
;                 int lane_k = lane_u; asm volatile("" : "+v"(lane_k));
;                 const int lr = lane_k & 15, q = lane_k >> 4;
; #pragma unroll
;                 for (int i = 0; i < 8; ++i) *(LAS f32x4*)(imp + lane_k * 32 + i * 4) = (f32x4){zf_, zf_, zf_, zf_};
;                 asm volatile("s_waitcnt lgkmcnt(0)" ::: "memory");
;                 __syncthreads();
;                 int tk = wave * 64 + lane_k; asm volatile("" : "+v"(tk));
;                 u32x4 rk = *(const GAS u32x4*)(gK + tk * 8);
;                 for (int tt = 0; tt < ntc; ++tt) {
;                     LAS bf16_t* Kt = Kb0 + (tt & 1) * 64 * 72;
;                     *(LAS u32x4*)(Kt + (tk >> 3) * 72 + (tk & 7) * 8) = rk;
;                     if (tt + 1 < ntc) rk = *(const GAS u32x4*)(gK + (size_t)(tt + 1) * 4096 + tk * 8);
.LBB0_986:
	s_waitcnt vmcnt(0)
	v_rcp_f32_e32 v76, v92
	v_cmp_lt_f32_e32 vcc, 0, v92
	s_nop 1
	v_cndmask_b32_e32 v128, 0, v76, vcc
	v_rcp_f32_e32 v76, v88
	v_cmp_lt_f32_e32 vcc, 0, v88
	s_nop 1
	v_cndmask_b32_e32 v127, 0, v76, vcc
	v_rcp_f32_e32 v76, v84
	v_cmp_lt_f32_e32 vcc, 0, v84
	s_nop 1
	v_cndmask_b32_e32 v126, 0, v76, vcc
	s_and_b64 vcc, exec, s[12:13]
	s_cbranch_vccz .LBB0_1008
	v_mov_b32_e32 v129, v204
	v_readlane_b32 s4, v255, 38
	v_lshl_add_u32 v76, v129, 7, s49
	ds_write_b128 v76, v[72:75] offset:46080
	ds_write_b128 v76, v[72:75] offset:46096
	ds_write_b128 v76, v[72:75] offset:46112
	ds_write_b128 v76, v[72:75] offset:46128
	ds_write_b128 v76, v[72:75] offset:46144
	ds_write_b128 v76, v[72:75] offset:46160
	ds_write_b128 v76, v[72:75] offset:46176
	ds_write_b128 v76, v[72:75] offset:46192
	v_add_u32_e32 v78, s4, v129
	s_waitcnt lgkmcnt(0)
	s_waitcnt lgkmcnt(0)
	s_barrier
	v_and_b32_e32 v130, 15, v129
	v_lshlrev_b32_e32 v76, 3, v78
	v_ashrrev_i32_e32 v77, 31, v76
	v_lshl_add_u64 v[88:89], v[76:77], 1, s[10:11]
	global_load_dwordx4 v[72:75], v[88:89], off
	v_ashrrev_i32_e32 v132, 4, v129
	v_lshrrev_b32_e32 v77, 3, v78
	s_movk_i32 s4, 0x90
	v_mul_lo_u32 v134, v77, s4
	v_and_b32_e32 v90, 56, v76
	v_add_u32_e32 v139, 4, v77
	v_and_b32_e32 v139, 8, v139
	v_xor_b32_e32 v90, v90, v139
	v_lshlrev_b32_e32 v131, 2, v132
	v_lshlrev_b32_e32 v133, 9, v130
	v_xor_b32_e32 v76, 0x80000000, v97
	v_xor_b32_e32 v80, 0x80000000, v98
	v_xor_b32_e32 v84, 0x80000000, v99
	v_readlane_b32 s4, v255, 41
	s_mov_b32 s6, 1
	v_and_b32_e32 v135, -16, v129
	v_mul_u32_u24_e32 v136, 0x90, v130
	v_add_u32_e32 v139, 4, v130
	v_and_b32_e32 v139, 8, v139
	v_lshlrev_b32_e32 v139, 1, v139
	v_xor_b32_e32 v135, v135, v139
	v_mov_b32_e32 v77, v76
	v_mov_b32_e32 v78, v76
	v_mov_b32_e32 v79, v76
	v_mov_b32_e32 v81, v80
	v_mov_b32_e32 v82, v80
	v_mov_b32_e32 v83, v80
	v_mov_b32_e32 v85, v84
	v_mov_b32_e32 v86, v84
	v_mov_b32_e32 v87, v84
	v_add3_u32 v137, v133, v131, s4
	v_lshl_add_u64 v[124:125], v[88:89], 0, s[22:23]
	s_mov_b32 s7, 0
	v_sub_u32_e32 v138, 0, v131
	v_lshlrev_b32_e32 v139, 1, v90
	v_mov_b32_e32 v140, v206
	v_mov_b32_e32 v141, v132
	s_branch .LBB0_990

; #define GAS __attribute__((address_space(1)))
; __device__ __forceinline__ void nsa_phase(LAS unsigned char* lds, const bf16_t* Q, const bf16_t* KVG, size_t kvg_stride, const bf16_t* kcc, const bf16_t* vcc, const float* G, bf16_t* cat,
;                                           int tid, int lane, int wave) {
;     ...
;                 float zs_ = 0.f; asm volatile("" : "+v"(zs_));
;                 int lane_c = lane_u; asm volatile("" : "+v"(lane_c));
;                 const int lr = lane_c & 15, q = lane_c >> 4;
; #pragma unroll
;                 for (int i = 0; i < 13; ++i) { const int e4 = lane_u + 64 * i; if (e4 < 816) *(LAS f32x4*)(Ssel + e4 * 4) = (f32x4){zs_, zs_, zs_, zs_}; }
;                 KVRegs R;
;                 __syncthreads();
;                 int tb = wave * 64 + lane_u; asm volatile("" : "+v"(tb));
;                 kv_fetch(R, gK + (size_t)nbeg * 4096, gV + (size_t)nbeg * 4096, tb, true);
;                 int kc_ = 0;
;                 const GAS bf16_t* Qw = (const GAS bf16_t*)(Qp + (size_t)(16 * wave) * 768);
;                 const unsigned w_own = selw[lr * 4 + q];
;                 for (int n = nbeg; n < nend; ++n) {
;                     LAS bf16_t* Kt = Kb0 + kc_ * 64 * 72; LAS bf16_t* Vt = Vb0 + kc_ * 64 * 72;
;                     kv_commit(R, Kt, Vt, tb, true);
;                     const bool bitn = ((w_own >> (n & 31)) & 1u) != 0u;
;                     const unsigned mask16 = (unsigned)((__builtin_amdgcn_ballot_w64(bitn) >> (16 * (n >> 5))) & 0xFFFFull);
;                     const int ksel = __builtin_popcount(mask16);
;                     const bool act = ((mask16 >> lr) & 1u) != 0u;
;                     if (act && q == 0) slist[__builtin_popcount(mask16 & ((1u << lr) - 1u))] = (unsigned)lr;
;                     asm volatile("s_waitcnt lgkmcnt(0)" ::: "memory");
;                     int jcg[3], rcg[3]; bool vg[3]; bf16x8 qB[3][2]; unsigned sl[3];
; #pragma unroll
;                     for (int gi = 0; gi < 3; ++gi) sl[gi] = slist[((16 * gi + lr) * 43) >> 7];
; #pragma unroll
;                     for (int gi = 0; gi < 3; ++gi) {
;                         const int cg = 16 * gi + lr, idx = (cg * 43) >> 7; rcg[gi] = cg - 3 * idx; vg[gi] = idx < ksel;
;                         jcg[gi] = vg[gi] ? (int)sl[gi] : 0;
;                         const GAS bf16_t* qg = Qw + (jcg[gi] * 768 + rcg[gi] * 64 + 8 * q);
.LBB0_1040:
	s_or_b64 exec, exec, s[2:3]
	s_mov_b64 s[2:3], exec
	v_readlane_b32 s4, v255, 50
	v_readlane_b32 s5, v255, 51
	s_and_b64 s[4:5], s[2:3], s[4:5]
	s_mov_b64 exec, s[4:5]
	ds_write_b128 v215, v[24:27] offset:52224
	s_or_b64 exec, exec, s[2:3]
	s_mov_b64 s[2:3], exec
	v_readlane_b32 s4, v255, 52
	v_readlane_b32 s5, v255, 53
	s_and_b64 s[4:5], s[2:3], s[4:5]
	s_mov_b64 exec, s[4:5]
	ds_write_b128 v215, v[24:27] offset:53248
	s_or_b64 exec, exec, s[2:3]
	s_mov_b64 s[2:3], exec
	v_readlane_b32 s4, v255, 54
	v_readlane_b32 s5, v255, 55
	s_and_b64 s[4:5], s[2:3], s[4:5]
	s_mov_b64 exec, s[4:5]
	ds_write_b128 v215, v[24:27] offset:54272
	s_or_b64 exec, exec, s[2:3]
	s_mov_b64 s[2:3], exec
	v_readlane_b32 s4, v255, 56
	v_readlane_b32 s5, v255, 57
	s_and_b64 s[4:5], s[2:3], s[4:5]
	s_mov_b64 exec, s[4:5]
	ds_write_b128 v215, v[24:27] offset:55296
	s_or_b64 exec, exec, s[2:3]
	s_mov_b64 s[2:3], exec
	v_readlane_b32 s4, v255, 58
	v_readlane_b32 s5, v255, 59
	s_and_b64 s[4:5], s[2:3], s[4:5]
	s_mov_b64 exec, s[4:5]
	ds_write_b128 v215, v[24:27] offset:56320
	s_or_b64 exec, exec, s[2:3]
	s_mov_b64 s[2:3], exec
	v_readlane_b32 s4, v255, 60
	v_readlane_b32 s5, v255, 61
	s_and_b64 s[4:5], s[2:3], s[4:5]
	s_mov_b64 exec, s[4:5]
	ds_write_b128 v215, v[24:27] offset:57344
	s_or_b64 exec, exec, s[2:3]
	s_mov_b64 s[2:3], exec
	v_readlane_b32 s4, v255, 62
	v_readlane_b32 s5, v255, 63
	s_and_b64 s[4:5], s[2:3], s[4:5]
	s_mov_b64 exec, s[4:5]
	ds_write_b128 v215, v[24:27] offset:58368
	s_or_b64 exec, exec, s[2:3]
	v_mov_b32_e32 v33, v207
	s_cmp_lt_i32 s38, s43
	s_waitcnt lgkmcnt(0)
	s_barrier
	s_cbranch_scc0 .LBB0_948
	s_lshl_b64 s[2:3], s[38:39], 13
	s_add_u32 s4, s34, s2
	v_lshlrev_b32_e32 v34, 3, v33
	s_addc_u32 s5, s35, s3
	v_ashrrev_i32_e32 v35, 31, v34
	s_add_u32 s2, s10, s2
	v_lshlrev_b64 v[36:37], 1, v[34:35]
	s_addc_u32 s3, s11, s3
	v_lshl_add_u64 v[24:25], s[4:5], 0, v[36:37]
	v_lshl_add_u64 v[28:29], s[2:3], 0, v[36:37]
	global_load_dwordx4 v[24:27], v[24:25], off
	v_and_b32_e32 v87, 15, v32
	global_load_dwordx4 v[28:31], v[28:29], off
	v_ashrrev_i32_e32 v35, 4, v32
	v_and_b32_e32 v39, 56, v34
	v_cmp_gt_u32_e64 s[68:69], 16, v32
	v_and_b32_e32 v97, -16, v32
	v_bfe_u32 v34, v32, 2, 2
	v_lshlrev_b32_e32 v32, 2, v32
	v_and_b32_e32 v40, 12, v32
	v_mul_u32_u24_e32 v32, 43, v87
	v_lshlrev_b32_e32 v38, 4, v87
	v_lshlrev_b32_e32 v89, 2, v35
	v_readlane_b32 s2, v255, 37
	v_lshrrev_b32_e32 v105, 7, v32
	v_mad_u32_u24 v32, v87, 43, v223
	v_add3_u32 v38, s2, v38, v89
	v_lshrrev_b32_e32 v33, 3, v33
	s_movk_i32 s2, 0x48
	v_lshrrev_b32_e32 v106, 7, v32
	v_mad_u32_u24 v32, v87, 43, v224
	ds_read_b32 v91, v38
	v_mul_lo_u32 v38, v33, s2
	v_or_b32_e32 v34, v89, v34
	s_movk_i32 s2, 0x90
	v_lshrrev_b32_e32 v108, 7, v32
	v_mul_i32_i24_e32 v32, -3, v106
	v_mul_lo_u32 v104, v34, s2
	v_add3_u32 v92, v32, v87, 16
	v_mul_i32_i24_e32 v32, -3, v108
	v_readlane_b32 s2, v255, 43
	v_add3_u32 v96, v32, v87, 32
	v_lshlrev_b32_e64 v33, v87, -1
	v_sub_u32_e32 v32, s2, v89
	s_lshl_b32 s2, s38, 6
	v_subrev_u32_e32 v111, s2, v32
	s_ashr_i32 s3, s38, 31
	s_mov_b32 s2, s38
	v_not_b32_e32 v95, v33
	v_lshlrev_b32_e32 v33, 3, v35
	v_mad_i32_i24 v88, v105, -3, v87
	s_lshl_b64 s[2:3], s[2:3], 13
	v_lshl_add_u32 v90, v88, 6, v33
	v_lshl_add_u32 v94, v92, 6, v33
	v_lshl_add_u32 v98, v96, 6, v33
	v_lshl_add_u64 v[32:33], s[2:3], 0, v[36:37]
	v_lshl_add_u64 v[34:35], s[10:11], 0, v[32:33]
	v_lshl_add_u64 v[32:33], s[34:35], 0, v[32:33]
	v_lshlrev_b32_e64 v93, v87, 1
	v_mul_u32_u24_e32 v99, 0x90, v87
	v_lshl_add_u32 v107, v106, 2, s27
	v_lshl_add_u32 v109, v108, 2, s27
	v_lshl_add_u32 v110, v105, 2, s27
	v_lshl_add_u64 v[100:101], v[34:35], 0, s[22:23]
	v_lshl_add_u64 v[102:103], v[32:33], 0, s[22:23]
	s_mov_b32 s8, 0
	v_lshlrev_b32_e32 v112, 1, v38
	v_lshlrev_b32_e32 v113, 1, v39
	v_lshlrev_b32_e32 v114, 1, v40
	v_lshrrev_b32_e32 v252, 3, v207
	v_add_u32_e32 v252, 4, v252
	v_and_b32_e32 v252, 8, v252
	v_lshlrev_b32_e32 v252, 1, v252
	v_xor_b32_e32 v113, v113, v252
	v_lshrrev_b32_e32 v252, 2, v204
	v_add_u32_e32 v252, 4, v252
	v_and_b32_e32 v252, 8, v252
	v_lshlrev_b32_e32 v252, 1, v252
	v_xor_b32_e32 v114, v114, v252
	v_add_u32_e32 v221, 4, v87
	v_and_b32_e32 v221, 8, v221
	v_lshlrev_b32_e32 v221, 1, v221
	v_xor_b32_e32 v221, v97, v221
	s_waitcnt lgkmcnt(0)
	s_and_b32 s2, s38, 31
	v_bfe_u32 v199, v91, s2, 1
	s_ashr_i32 s2, s38, 1
	v_cmp_ne_u32_e32 vcc, 0, v199
	s_and_b32 s2, s2, -16
	s_lshr_b64 s[2:3], vcc, s2
	v_and_b32_e32 v199, s2, v93
	v_cmp_ne_u32_e32 vcc, 0, v199
	s_and_b32 s4, s2, 0xffff
	s_bcnt1_i32_b32 s100, s4
	s_and_b64 vcc, vcc, s[68:69]
	s_and_saveexec_b64 s[4:5], vcc
	v_and_b32_e32 v199, s2, v95
	v_bcnt_u32_b32 v199, v199, 0
	v_lshl_add_u32 v199, v199, 2, s27
	ds_write_b32 v199, v87
	s_or_b64 exec, exec, s[4:5]
	s_cmp_eq_u32 s100, 0
	s_cbranch_scc1 .Lsp_gdone_pre
	s_waitcnt lgkmcnt(0)
	ds_read_b32 v200, v107
	ds_read_b32 v199, v109
	v_cmp_gt_u32_e64 s[4:5], s100, v105
	v_mov_b32_e32 v196, 0
	s_nop 0
	s_and_saveexec_b64 s[2:3], s[4:5]
	ds_read_b32 v196, v110
	s_or_b64 exec, exec, s[2:3]
	s_waitcnt lgkmcnt(0)
	v_mad_u64_u32 v[202:203], s[2:3], v196, s48, v[90:91]
	v_ashrrev_i32_e32 v203, 31, v202
	v_cmp_gt_u32_e64 s[4:5], s100, v106
	v_cmp_gt_u32_e64 vcc, s100, v108
	v_lshl_add_u64 v[202:203], v[202:203], 1, s[30:31]
	s_nop 0
	v_cndmask_b32_e64 v197, 0, v200, s[4:5]
	v_cndmask_b32_e64 v198, 0, v199, vcc
	global_load_dwordx4 v[228:231], v[202:203], off
	global_load_dwordx4 v[232:235], v[202:203], off offset:64
	s_cmp_lt_u32 s100, 6
	s_cbranch_scc1 .Lsp_gdone_pre
	v_mad_u64_u32 v[202:203], s[2:3], v197, s48, v[94:95]
	v_ashrrev_i32_e32 v203, 31, v202
	v_lshl_add_u64 v[202:203], v[202:203], 1, s[30:31]
	global_load_dwordx4 v[236:239], v[202:203], off
	global_load_dwordx4 v[240:243], v[202:203], off offset:64
	s_cmp_lt_u32 s100, 11
	s_cbranch_scc1 .Lsp_gdone_pre
	v_mad_u64_u32 v[216:217], s[2:3], v198, s48, v[98:99]
	v_ashrrev_i32_e32 v217, 31, v216
	v_lshl_add_u64 v[216:217], v[216:217], 1, s[30:31]
	global_load_dwordx4 v[244:247], v[216:217], off
	global_load_dwordx4 v[248:251], v[216:217], off offset:64

; #define LAS __attribute__((address_space(3)))
; #define MFMA16(a, b, c) __builtin_amdgcn_mfma_f32_16x16x32_bf16((a), (b), (c), 0, 0, 0)
; __device__ __forceinline__ void sel_group(const LAS bf16_t* Kt, const LAS bf16_t* Vt, LAS float* S, const bf16x8 qB0, const bf16x8 qB1, int jc, int rc, bool valid, bool masked, int tw64, int lr, int q) {
;     LAS float* Srow = S + (jc * 3 + rc) * 68;
;     const float mref = Srow[65]; const bool st = Srow[66] != 0.f;
;     f32x4 acc[4];
; #pragma unroll
;     for (int dt = 0; dt < 4; ++dt) acc[dt] = *(const LAS f32x4*)(Srow + 16 * dt + 4 * q);
;     float lc = Srow[64];
;     const float nm = valid ? -mref : -1e30f;
;     const f32x4 c0 = (f32x4){nm, nm, nm, nm};
;     const LAS bf16_t* kbase = Kt + lr * 72 + 8 * q;
;     f32x4 s[4];
;     {
;         bf16x8 kf[2][2];
;         kf[0][0] = *(const LAS bf16x8*)(kbase); kf[0][1] = *(const LAS bf16x8*)(kbase + 32);
; #pragma unroll
;         for (int mt = 0; mt < 4; ++mt) {
;             if (mt < 3) { kf[(mt + 1) & 1][0] = *(const LAS bf16x8*)(kbase + 16 * (mt + 1) * 72); kf[(mt + 1) & 1][1] = *(const LAS bf16x8*)(kbase + 16 * (mt + 1) * 72 + 32); }
;             __builtin_amdgcn_sched_barrier(0);
;             __builtin_amdgcn_s_setprio(1); s[mt] = MFMA16(kf[mt & 1][0], qB0, c0); s[mt] = MFMA16(kf[mt & 1][1], qB1, s[mt]); __builtin_amdgcn_s_setprio(0);
;             __builtin_amdgcn_sched_barrier(0);
;         }
;     }
;     if (masked) {
;         const int hq = tw64 + jc - 4 * q;
; #pragma unroll
;         for (int mt = 0; mt < 4; ++mt)
; #pragma unroll
;             for (int i = 0; i < 4; ++i) s[mt][i] = ((16 * mt + i) <= hq) ? s[mt][i] : -1e30f;
.Lsp_gdone_loop:
	s_waitcnt lgkmcnt(0)
	s_cmp_eq_u32 s101, 1
	s_cselect_b64 s[2:3], -1, 0
	s_cmp_eq_u32 s45, s38
	s_cselect_b64 s[12:13], -1, 0
	v_add_u32_e32 v48, s6, v99
	v_add_u32_e32 v117, v48, v221
	v_cndmask_b32_e64 v48, 0, 1, s[12:13]
	v_add3_u32 v115, s6, v104, v114
	s_cmp_eq_u32 s10, 0
	v_cmp_ne_u32_e64 s[72:73], 1, v48
	s_barrier
	s_cbranch_scc1 .LBB0_1078
	v_mad_u64_u32 v[48:49], s[4:5], v120, 3, v[88:89]
	v_mul_lo_u32 v48, v48, s36
	v_add_u32_e32 v119, s49, v48
	v_add_u32_e32 v48, v119, v97
	ds_read_b96 v[84:86], v119 offset:46336
	ds_read_b128 v[60:63], v48 offset:46080
	ds_read_b128 v[56:59], v48 offset:46144
	ds_read_b128 v[52:55], v48 offset:46208
	ds_read_b128 v[48:51], v48 offset:46272
	ds_read_b128 v[64:67], v117
	ds_read_b128 v[68:71], v117 offset:64
	ds_read_b128 v[72:75], v117 offset:2304
	ds_read_b128 v[122:125], v117 offset:2368
	s_waitcnt lgkmcnt(8)
	v_cndmask_b32_e64 v126, v222, -v85, s[76:77]
	v_mov_b32_e32 v127, v126
	v_mov_b32_e32 v128, v126
	v_mov_b32_e32 v129, v126
	s_setprio 1
	s_waitcnt lgkmcnt(3)
	v_mfma_f32_16x16x32_bf16 v[64:67], v[64:67], v[76:79], v[126:129]
	s_waitcnt lgkmcnt(2)
	v_mfma_f32_16x16x32_bf16 v[64:67], v[68:71], v[80:83], v[64:67]
	s_setprio 0
	ds_read_b128 v[130:133], v117 offset:4608
	ds_read_b128 v[134:137], v117 offset:4672
	s_setprio 1
	s_waitcnt lgkmcnt(3)
	v_mfma_f32_16x16x32_bf16 v[68:71], v[72:75], v[76:79], v[126:129]
	s_waitcnt lgkmcnt(2)
	v_mfma_f32_16x16x32_bf16 v[68:71], v[122:125], v[80:83], v[68:71]
	s_setprio 0
	ds_read_b128 v[122:125], v117 offset:6912
	ds_read_b128 v[138:141], v117 offset:6976
	s_setprio 1
	s_waitcnt lgkmcnt(3)
	v_mfma_f32_16x16x32_bf16 v[72:75], v[130:133], v[76:79], v[126:129]
	s_waitcnt lgkmcnt(2)
	v_mfma_f32_16x16x32_bf16 v[72:75], v[134:137], v[80:83], v[72:75]
	s_setprio 0
	s_setprio 1
	s_waitcnt lgkmcnt(1)
	v_mfma_f32_16x16x32_bf16 v[76:79], v[122:125], v[76:79], v[126:129]
	s_waitcnt lgkmcnt(0)
	v_mfma_f32_16x16x32_bf16 v[76:79], v[138:141], v[80:83], v[76:79]
	s_setprio 0
	s_and_b64 vcc, exec, s[72:73]
	s_cbranch_vccnz .LBB0_1067
	v_add_u32_e32 v80, v120, v111
	v_cmp_lt_i32_e32 vcc, -1, v80
	s_nop 1
	v_cndmask_b32_e32 v64, v222, v64, vcc
	v_cmp_lt_i32_e32 vcc, 0, v80
	s_nop 1
	v_cndmask_b32_e32 v65, v222, v65, vcc
	v_cmp_lt_i32_e32 vcc, 1, v80
	s_nop 1
	v_cndmask_b32_e32 v66, v222, v66, vcc
	v_cmp_lt_i32_e32 vcc, 2, v80
	s_nop 1
	v_cndmask_b32_e32 v67, v222, v67, vcc
	v_cmp_lt_i32_e32 vcc, 15, v80
	s_nop 1
	v_cndmask_b32_e32 v68, v222, v68, vcc
	v_cmp_lt_i32_e32 vcc, 16, v80
	s_nop 1
	v_cndmask_b32_e32 v69, v222, v69, vcc
	v_cmp_lt_i32_e32 vcc, 17, v80
	s_nop 1
	v_cndmask_b32_e32 v70, v222, v70, vcc
	v_cmp_lt_i32_e32 vcc, 18, v80
	s_nop 1
	v_cndmask_b32_e32 v71, v222, v71, vcc
	v_cmp_lt_i32_e32 vcc, 31, v80
	s_nop 1
	v_cndmask_b32_e32 v72, v222, v72, vcc
	v_cmp_lt_i32_e32 vcc, 32, v80
	s_nop 1
	v_cndmask_b32_e32 v73, v222, v73, vcc
	v_cmp_lt_i32_e32 vcc, 33, v80
	s_nop 1
	v_cndmask_b32_e32 v74, v222, v74, vcc
	v_cmp_lt_i32_e32 vcc, 34, v80
	s_nop 1
	v_cndmask_b32_e32 v75, v222, v75, vcc
	v_cmp_lt_i32_e32 vcc, 47, v80
	s_nop 1
	v_cndmask_b32_e32 v76, v222, v76, vcc
	v_cmp_lt_i32_e32 vcc, 48, v80
	s_nop 1
	v_cndmask_b32_e32 v77, v222, v77, vcc
	v_cmp_lt_i32_e32 vcc, 49, v80
	s_nop 1
	v_cndmask_b32_e32 v78, v222, v78, vcc
	v_cmp_lt_i32_e32 vcc, 50, v80
	s_nop 1
	v_cndmask_b32_e32 v79, v222, v79, vcc
